# MoBA loop: LDS-DMA issue de-synchronised between the two wave groups (group 0 right after the barrier, group 1 between the PV and QK MFMAs)
# speedup vs baseline: 1.0750x; 1.0750x over previous
.LBB0_1059:
.LBB0_1060:
.LBB0_1062:
.Lmb1_A:
	s_barrier
	s_and_b64 vcc, exec, s[6:7]
	s_cbranch_vccz .Lmb1_A_g1top
	s_add_i32 s45, s37, 1
	s_cmp_ge_u32 s45, s30
	s_cbranch_scc1 .Lmb1_skKA
	s_add_i32 s45, s44, 0x2000
	s_and_b32 s45, s45, 0x6000
	s_add_i32 s45, s45, s74
	s_mov_b32 s99, m0
	s_mov_b32 m0, s45
	s_nop 0
	global_load_lds_dwordx4 v[114:115], off
	s_mov_b32 m0, s99
	s_mov_b32 s43, 1

; #define ATT_MFMA(a, b, c) __builtin_amdgcn_mfma_f32_32x32x16_bf16((a), (b), (c), 0, 0, 0)
; __device__ __forceinline__ void pv(f32x16* o, int vb, bf16x8 pa0, bf16x8 pa1, bf16x8 pa2, bf16x8 pa3) {
; #pragma unroll
;     for (int d0 = 0; d0 < 2; ++d0) { s16x4 lo[4], hi[4];
; #pragma unroll
;         for (int ks = 0; ks < 4; ++ks) {
;             asm volatile("ds_read_b64_tr_b16 %0,%1 offset:%c2" : "=&v"(lo[ks]) : "v"(vb), "i"(d0 * 4096 + ks * 1024) : "memory");
;             asm volatile("ds_read_b64_tr_b16 %0,%1 offset:%c2" : "=&v"(hi[ks]) : "v"(vb), "i"(d0 * 4096 + ks * 1024 + 512) : "memory"); }
;         asm volatile("s_waitcnt lgkmcnt(0)" ::: "memory"); __builtin_amdgcn_sched_barrier(0);
;     ...
;         o[d0] = ATT_MFMA(pa0, ATT_PK(0), o[d0]);
;         o[d0] = ATT_MFMA(pa1, ATT_PK(1), o[d0]);
;         o[d0] = ATT_MFMA(pa2, ATT_PK(2), o[d0]);
;         o[d0] = ATT_MFMA(pa3, ATT_PK(3), o[d0]);
.Lmb1_skVA:
.Lmb1_A_g1top:
	s_add_i32 s42, s44, 0x2000
	s_add_i32 s98, s44, 0x4000
	s_and_b32 s45, s98, 0x6000
	v_add_u32_e32 v133, s45, v130
	ds_read_b128 v[154:157], v133
	ds_read_b128 v[158:161], v133 offset:512
	ds_read_b128 v[162:165], v133 offset:2048
	ds_read_b128 v[166:169], v133 offset:2560
	ds_read_b128 v[170:173], v133 offset:4096
	ds_read_b128 v[174:177], v133 offset:4608
	ds_read_b128 v[178:181], v133 offset:6144
	ds_read_b128 v[182:185], v133 offset:6656
	s_and_b32 s45, s42, 0x6000
	v_add_u32_e32 v218, s45, v132
	s_add_i32 s98, s34, 2
	s_cmp_ge_i32 s34, s31
	s_cbranch_scc1 .Lmb1_A_near
	v_mfma_f32_32x32x16_bf16 v[16:31], v[108:111], v[186:189], v[16:31]
	v_exp_f32_e32 v64, v64
	v_exp_f32_e32 v48, v48
	v_mfma_f32_32x32x16_bf16 v[16:31], v[104:107], v[190:193], v[16:31]
	v_exp_f32_e32 v65, v65
	v_exp_f32_e32 v49, v49
	v_add_f32_e32 v252, v64, v48
	v_mfma_f32_32x32x16_bf16 v[16:31], v[100:103], v[194:197], v[16:31]
	v_exp_f32_e32 v66, v66
	v_exp_f32_e32 v50, v50
	v_add_f32_e32 v253, v65, v49
	v_add_f32_e32 v252, v252, v253
	v_mfma_f32_32x32x16_bf16 v[16:31], v[96:99], v[198:201], v[16:31]
	v_exp_f32_e32 v67, v67
	v_exp_f32_e32 v51, v51
	v_add_f32_e32 v253, v66, v50
	v_add_f32_e32 v252, v252, v253
	v_mfma_f32_32x32x16_bf16 v[32:47], v[108:111], v[202:205], v[32:47]
	v_exp_f32_e32 v68, v68
	v_exp_f32_e32 v52, v52
	v_add_f32_e32 v253, v67, v51
	v_add_f32_e32 v252, v252, v253
	ds_read_b64_tr_b16 v[186:187], v218
	ds_read_b64_tr_b16 v[188:189], v218 offset:512
	v_mfma_f32_32x32x16_bf16 v[32:47], v[104:107], v[206:209], v[32:47]
	v_exp_f32_e32 v69, v69
	v_exp_f32_e32 v53, v53
	v_add_f32_e32 v253, v68, v52
	v_add_f32_e32 v252, v252, v253
	ds_read_b64_tr_b16 v[190:191], v218 offset:1024
	ds_read_b64_tr_b16 v[192:193], v218 offset:1536
	v_mfma_f32_32x32x16_bf16 v[32:47], v[100:103], v[210:213], v[32:47]
	v_exp_f32_e32 v70, v70
	v_exp_f32_e32 v54, v54
	v_add_f32_e32 v253, v69, v53
	v_add_f32_e32 v252, v252, v253
	ds_read_b64_tr_b16 v[194:195], v218 offset:2048
	ds_read_b64_tr_b16 v[196:197], v218 offset:2560
	v_mfma_f32_32x32x16_bf16 v[32:47], v[96:99], v[214:217], v[32:47]
	v_exp_f32_e32 v71, v71
	v_exp_f32_e32 v55, v55
	v_add_f32_e32 v253, v70, v54
	v_add_f32_e32 v252, v252, v253
	ds_read_b64_tr_b16 v[198:199], v218 offset:3072
	ds_read_b64_tr_b16 v[200:201], v218 offset:3584
	s_and_b64 vcc, exec, s[6:7]
	s_cbranch_vccnz .Lmb1_A_g0mid
	s_add_i32 s45, s37, 1
	s_cmp_ge_u32 s45, s30
	s_cbranch_scc1 .Lmb1_skKAm
	s_add_i32 s45, s44, 0x2000
	s_and_b32 s45, s45, 0x6000
	s_add_i32 s45, s45, s74
	s_mov_b32 s99, m0
	s_mov_b32 m0, s45
	s_nop 0
	global_load_lds_dwordx4 v[114:115], off
	s_mov_b32 m0, s99
	s_mov_b32 s43, 1

; #define ATT_MFMA(a, b, c) __builtin_amdgcn_mfma_f32_32x32x16_bf16((a), (b), (c), 0, 0, 0)
; #define ATT_RD128(dst, addr, off) asm volatile("ds_read_b128 %0, %1 offset:%c2" : "=&v"(dst) : "v"(addr), "i"(off) : "memory")
; template <bool DO_QK, bool DO_PV> __device__ __forceinline__ void mseg(f32x16& p0, f32x16& p1, f32x16* o, unsigned kaddr, unsigned vaddr, const bf16x8* qr, const f32x16& cin,
;                                                                      bf16x8 pa0, bf16x8 pa1, bf16x8 pa2, bf16x8 pa3) {
;     ...
;         p0 = ATT_MFMA(kf[0], qr[0], cin); p1 = ATT_MFMA(kf[1], qr[0], cin);
;         p0 = ATT_MFMA(kf[2], qr[1], p0);  p1 = ATT_MFMA(kf[3], qr[1], p1);
;         __builtin_amdgcn_sched_barrier(0);
;         ATT_RD128(kf[0], kaddr, 4096); ATT_RD128(kf[1], kaddr, 4608); ATT_RD128(kf[2], kaddr, 6144); ATT_RD128(kf[3], kaddr, 6656);
;         asm volatile("s_waitcnt lgkmcnt(0)" : "+v"(kf[0]), "+v"(kf[1]), "+v"(kf[2]), "+v"(kf[3]), "+v"(vl[0]), "+v"(vh[0]), "+v"(vl[1]), "+v"(vh[1]), "+v"(vl[2]), "+v"(vh[2]), "+v"(vl[3]), "+v"(vh[3]) :: "memory");
;         __builtin_amdgcn_sched_barrier(0);
;         p0 = ATT_MFMA(kf[0], qr[2], p0);  p1 = ATT_MFMA(kf[1], qr[2], p1);
;         p0 = ATT_MFMA(kf[2], qr[3], p0);  p1 = ATT_MFMA(kf[3], qr[3], p1);
.Lmb1_skVAm:
.Lmb1_A_g0mid:
	s_waitcnt lgkmcnt(8)
	v_mfma_f32_32x32x16_bf16 v[236:251], v[154:157], v[92:95], v[220:235]
	v_exp_f32_e32 v72, v72
	v_exp_f32_e32 v56, v56
	v_add_f32_e32 v253, v71, v55
	v_add_f32_e32 v252, v252, v253
	v_cvt_pk_bf16_f32 v108, v64, v65
	v_cvt_pk_bf16_f32 v100, v48, v49
	ds_read_b64_tr_b16 v[202:203], v218 offset:4096
	ds_read_b64_tr_b16 v[204:205], v218 offset:4608
	v_mfma_f32_32x32x16_bf16 v[134:149], v[158:161], v[92:95], v[220:235]
	v_exp_f32_e32 v73, v73
	v_exp_f32_e32 v57, v57
	v_add_f32_e32 v253, v72, v56
	v_add_f32_e32 v252, v252, v253
	v_cvt_pk_bf16_f32 v109, v66, v67
	v_cvt_pk_bf16_f32 v101, v50, v51
	ds_read_b64_tr_b16 v[206:207], v218 offset:5120
	ds_read_b64_tr_b16 v[208:209], v218 offset:5632
	v_mfma_f32_32x32x16_bf16 v[236:251], v[162:165], v[88:91], v[236:251]
	v_exp_f32_e32 v74, v74
	v_exp_f32_e32 v58, v58
	v_add_f32_e32 v253, v73, v57
	v_add_f32_e32 v252, v252, v253
	v_cvt_pk_bf16_f32 v110, v68, v69
	v_cvt_pk_bf16_f32 v102, v52, v53
	ds_read_b64_tr_b16 v[210:211], v218 offset:6144
	ds_read_b64_tr_b16 v[212:213], v218 offset:6656
	v_mfma_f32_32x32x16_bf16 v[134:149], v[166:169], v[88:91], v[134:149]
	v_exp_f32_e32 v75, v75
	v_exp_f32_e32 v59, v59
	v_add_f32_e32 v253, v74, v58
	v_add_f32_e32 v252, v252, v253
	v_cvt_pk_bf16_f32 v111, v70, v71
	v_cvt_pk_bf16_f32 v103, v54, v55
	ds_read_b64_tr_b16 v[214:215], v218 offset:7168
	ds_read_b64_tr_b16 v[216:217], v218 offset:7680
	v_mfma_f32_32x32x16_bf16 v[236:251], v[170:173], v[84:87], v[236:251]
	v_exp_f32_e32 v76, v76
	v_exp_f32_e32 v60, v60
	v_add_f32_e32 v253, v75, v59
	v_add_f32_e32 v252, v252, v253
	v_cvt_pk_bf16_f32 v104, v72, v73
	v_cvt_pk_bf16_f32 v96, v56, v57
	v_mfma_f32_32x32x16_bf16 v[134:149], v[174:177], v[84:87], v[134:149]
	v_exp_f32_e32 v77, v77
	v_exp_f32_e32 v61, v61
	v_add_f32_e32 v253, v76, v60
	v_add_f32_e32 v252, v252, v253
	v_cvt_pk_bf16_f32 v105, v74, v75
	v_cvt_pk_bf16_f32 v97, v58, v59
	v_mfma_f32_32x32x16_bf16 v[236:251], v[178:181], v[80:83], v[236:251]
	v_exp_f32_e32 v78, v78
	v_exp_f32_e32 v62, v62
	v_add_f32_e32 v253, v77, v61
	v_add_f32_e32 v252, v252, v253
	v_cvt_pk_bf16_f32 v106, v76, v77
	v_cvt_pk_bf16_f32 v98, v60, v61
	v_mfma_f32_32x32x16_bf16 v[134:149], v[182:185], v[80:83], v[134:149]
	v_exp_f32_e32 v79, v79
	v_exp_f32_e32 v63, v63
	v_add_f32_e32 v253, v78, v62
	v_add_f32_e32 v252, v252, v253
	v_add_f32_e32 v253, v79, v63
	v_add_f32_e32 v252, v252, v253
	v_cvt_pk_bf16_f32 v107, v78, v79
	v_cvt_pk_bf16_f32 v99, v62, v63
	v_add_f32_e32 v131, v131, v252

.Lmb1_B:
	s_barrier
	s_and_b64 vcc, exec, s[6:7]
	s_cbranch_vccz .Lmb1_B_g1top
	s_add_i32 s45, s37, 1
	s_cmp_ge_u32 s45, s30
	s_cbranch_scc1 .Lmb1_skKB
	s_add_i32 s45, s44, 0x2000
	s_and_b32 s45, s45, 0x6000
	s_add_i32 s45, s45, s74
	s_mov_b32 s99, m0
	s_mov_b32 m0, s45
	s_nop 0
	global_load_lds_dwordx4 v[114:115], off
	s_mov_b32 m0, s99
	s_mov_b32 s43, 1

; #define ATT_MFMA(a, b, c) __builtin_amdgcn_mfma_f32_32x32x16_bf16((a), (b), (c), 0, 0, 0)
; __device__ __forceinline__ void pv(f32x16* o, int vb, bf16x8 pa0, bf16x8 pa1, bf16x8 pa2, bf16x8 pa3) {
; #pragma unroll
;     for (int d0 = 0; d0 < 2; ++d0) { s16x4 lo[4], hi[4];
; #pragma unroll
;         for (int ks = 0; ks < 4; ++ks) {
;             asm volatile("ds_read_b64_tr_b16 %0,%1 offset:%c2" : "=&v"(lo[ks]) : "v"(vb), "i"(d0 * 4096 + ks * 1024) : "memory");
;             asm volatile("ds_read_b64_tr_b16 %0,%1 offset:%c2" : "=&v"(hi[ks]) : "v"(vb), "i"(d0 * 4096 + ks * 1024 + 512) : "memory"); }
;         asm volatile("s_waitcnt lgkmcnt(0)" ::: "memory"); __builtin_amdgcn_sched_barrier(0);
;     ...
;         o[d0] = ATT_MFMA(pa0, ATT_PK(0), o[d0]);
;         o[d0] = ATT_MFMA(pa1, ATT_PK(1), o[d0]);
;         o[d0] = ATT_MFMA(pa2, ATT_PK(2), o[d0]);
;         o[d0] = ATT_MFMA(pa3, ATT_PK(3), o[d0]);
.Lmb1_skVB:
.Lmb1_B_g1top:
	s_add_i32 s42, s44, 0x2000
	s_add_i32 s98, s44, 0x4000
	s_and_b32 s45, s98, 0x6000
	v_add_u32_e32 v133, s45, v130
	ds_read_b128 v[154:157], v133
	ds_read_b128 v[158:161], v133 offset:512
	ds_read_b128 v[162:165], v133 offset:2048
	ds_read_b128 v[166:169], v133 offset:2560
	ds_read_b128 v[170:173], v133 offset:4096
	ds_read_b128 v[174:177], v133 offset:4608
	ds_read_b128 v[178:181], v133 offset:6144
	ds_read_b128 v[182:185], v133 offset:6656
	s_and_b32 s45, s42, 0x6000
	v_add_u32_e32 v218, s45, v132
	s_add_i32 s98, s34, 2
	s_cmp_ge_i32 s34, s31
	s_cbranch_scc1 .Lmb1_B_near
	v_mfma_f32_32x32x16_bf16 v[16:31], v[108:111], v[186:189], v[16:31]
	v_exp_f32_e32 v236, v236
	v_exp_f32_e32 v134, v134
	v_mfma_f32_32x32x16_bf16 v[16:31], v[104:107], v[190:193], v[16:31]
	v_exp_f32_e32 v237, v237
	v_exp_f32_e32 v135, v135
	v_add_f32_e32 v252, v236, v134
	v_mfma_f32_32x32x16_bf16 v[16:31], v[100:103], v[194:197], v[16:31]
	v_exp_f32_e32 v238, v238
	v_exp_f32_e32 v136, v136
	v_add_f32_e32 v253, v237, v135
	v_add_f32_e32 v252, v252, v253
	v_mfma_f32_32x32x16_bf16 v[16:31], v[96:99], v[198:201], v[16:31]
	v_exp_f32_e32 v239, v239
	v_exp_f32_e32 v137, v137
	v_add_f32_e32 v253, v238, v136
	v_add_f32_e32 v252, v252, v253
	v_mfma_f32_32x32x16_bf16 v[32:47], v[108:111], v[202:205], v[32:47]
	v_exp_f32_e32 v240, v240
	v_exp_f32_e32 v138, v138
	v_add_f32_e32 v253, v239, v137
	v_add_f32_e32 v252, v252, v253
	ds_read_b64_tr_b16 v[186:187], v218
	ds_read_b64_tr_b16 v[188:189], v218 offset:512
	v_mfma_f32_32x32x16_bf16 v[32:47], v[104:107], v[206:209], v[32:47]
	v_exp_f32_e32 v241, v241
	v_exp_f32_e32 v139, v139
	v_add_f32_e32 v253, v240, v138
	v_add_f32_e32 v252, v252, v253
	ds_read_b64_tr_b16 v[190:191], v218 offset:1024
	ds_read_b64_tr_b16 v[192:193], v218 offset:1536
	v_mfma_f32_32x32x16_bf16 v[32:47], v[100:103], v[210:213], v[32:47]
	v_exp_f32_e32 v242, v242
	v_exp_f32_e32 v140, v140
	v_add_f32_e32 v253, v241, v139
	v_add_f32_e32 v252, v252, v253
	ds_read_b64_tr_b16 v[194:195], v218 offset:2048
	ds_read_b64_tr_b16 v[196:197], v218 offset:2560
	v_mfma_f32_32x32x16_bf16 v[32:47], v[96:99], v[214:217], v[32:47]
	v_exp_f32_e32 v243, v243
	v_exp_f32_e32 v141, v141
	v_add_f32_e32 v253, v242, v140
	v_add_f32_e32 v252, v252, v253
	ds_read_b64_tr_b16 v[198:199], v218 offset:3072
	ds_read_b64_tr_b16 v[200:201], v218 offset:3584
	s_and_b64 vcc, exec, s[6:7]
	s_cbranch_vccnz .Lmb1_B_g0mid
	s_add_i32 s45, s37, 1
	s_cmp_ge_u32 s45, s30
	s_cbranch_scc1 .Lmb1_skKBm
	s_add_i32 s45, s44, 0x2000
	s_and_b32 s45, s45, 0x6000
	s_add_i32 s45, s45, s74
	s_mov_b32 s99, m0
	s_mov_b32 m0, s45
	s_nop 0
	global_load_lds_dwordx4 v[114:115], off
	s_mov_b32 m0, s99
	s_mov_b32 s43, 1

; #define ATT_MFMA(a, b, c) __builtin_amdgcn_mfma_f32_32x32x16_bf16((a), (b), (c), 0, 0, 0)
; #define ATT_RD128(dst, addr, off) asm volatile("ds_read_b128 %0, %1 offset:%c2" : "=&v"(dst) : "v"(addr), "i"(off) : "memory")
; template <bool DO_QK, bool DO_PV> __device__ __forceinline__ void mseg(f32x16& p0, f32x16& p1, f32x16* o, unsigned kaddr, unsigned vaddr, const bf16x8* qr, const f32x16& cin,
;                                                                      bf16x8 pa0, bf16x8 pa1, bf16x8 pa2, bf16x8 pa3) {
;     ...
;         p0 = ATT_MFMA(kf[0], qr[0], cin); p1 = ATT_MFMA(kf[1], qr[0], cin);
;         p0 = ATT_MFMA(kf[2], qr[1], p0);  p1 = ATT_MFMA(kf[3], qr[1], p1);
;         __builtin_amdgcn_sched_barrier(0);
;         ATT_RD128(kf[0], kaddr, 4096); ATT_RD128(kf[1], kaddr, 4608); ATT_RD128(kf[2], kaddr, 6144); ATT_RD128(kf[3], kaddr, 6656);
;         asm volatile("s_waitcnt lgkmcnt(0)" : "+v"(kf[0]), "+v"(kf[1]), "+v"(kf[2]), "+v"(kf[3]), "+v"(vl[0]), "+v"(vh[0]), "+v"(vl[1]), "+v"(vh[1]), "+v"(vl[2]), "+v"(vh[2]), "+v"(vl[3]), "+v"(vh[3]) :: "memory");
;         __builtin_amdgcn_sched_barrier(0);
;         p0 = ATT_MFMA(kf[0], qr[2], p0);  p1 = ATT_MFMA(kf[1], qr[2], p1);
;         p0 = ATT_MFMA(kf[2], qr[3], p0);  p1 = ATT_MFMA(kf[3], qr[3], p1);
.Lmb1_skVBm:
.Lmb1_B_g0mid:
	s_waitcnt lgkmcnt(8)
	v_mfma_f32_32x32x16_bf16 v[64:79], v[154:157], v[92:95], v[220:235]
	v_exp_f32_e32 v244, v244
	v_exp_f32_e32 v142, v142
	v_add_f32_e32 v253, v243, v141
	v_add_f32_e32 v252, v252, v253
	v_cvt_pk_bf16_f32 v108, v236, v237
	v_cvt_pk_bf16_f32 v100, v134, v135
	ds_read_b64_tr_b16 v[202:203], v218 offset:4096
	ds_read_b64_tr_b16 v[204:205], v218 offset:4608
	v_mfma_f32_32x32x16_bf16 v[48:63], v[158:161], v[92:95], v[220:235]
	v_exp_f32_e32 v245, v245
	v_exp_f32_e32 v143, v143
	v_add_f32_e32 v253, v244, v142
	v_add_f32_e32 v252, v252, v253
	v_cvt_pk_bf16_f32 v109, v238, v239
	v_cvt_pk_bf16_f32 v101, v136, v137
	ds_read_b64_tr_b16 v[206:207], v218 offset:5120
	ds_read_b64_tr_b16 v[208:209], v218 offset:5632
	v_mfma_f32_32x32x16_bf16 v[64:79], v[162:165], v[88:91], v[64:79]
	v_exp_f32_e32 v246, v246
	v_exp_f32_e32 v144, v144
	v_add_f32_e32 v253, v245, v143
	v_add_f32_e32 v252, v252, v253
	v_cvt_pk_bf16_f32 v110, v240, v241
	v_cvt_pk_bf16_f32 v102, v138, v139
	ds_read_b64_tr_b16 v[210:211], v218 offset:6144
	ds_read_b64_tr_b16 v[212:213], v218 offset:6656
	v_mfma_f32_32x32x16_bf16 v[48:63], v[166:169], v[88:91], v[48:63]
	v_exp_f32_e32 v247, v247
	v_exp_f32_e32 v145, v145
	v_add_f32_e32 v253, v246, v144
	v_add_f32_e32 v252, v252, v253
	v_cvt_pk_bf16_f32 v111, v242, v243
	v_cvt_pk_bf16_f32 v103, v140, v141
	ds_read_b64_tr_b16 v[214:215], v218 offset:7168
	ds_read_b64_tr_b16 v[216:217], v218 offset:7680
	v_mfma_f32_32x32x16_bf16 v[64:79], v[170:173], v[84:87], v[64:79]
	v_exp_f32_e32 v248, v248
	v_exp_f32_e32 v146, v146
	v_add_f32_e32 v253, v247, v145
	v_add_f32_e32 v252, v252, v253
	v_cvt_pk_bf16_f32 v104, v244, v245
	v_cvt_pk_bf16_f32 v96, v142, v143
	v_mfma_f32_32x32x16_bf16 v[48:63], v[174:177], v[84:87], v[48:63]
	v_exp_f32_e32 v249, v249
	v_exp_f32_e32 v147, v147
	v_add_f32_e32 v253, v248, v146
	v_add_f32_e32 v252, v252, v253
	v_cvt_pk_bf16_f32 v105, v246, v247
	v_cvt_pk_bf16_f32 v97, v144, v145
	v_mfma_f32_32x32x16_bf16 v[64:79], v[178:181], v[80:83], v[64:79]
	v_exp_f32_e32 v250, v250
	v_exp_f32_e32 v148, v148
	v_add_f32_e32 v253, v249, v147
	v_add_f32_e32 v252, v252, v253
	v_cvt_pk_bf16_f32 v106, v248, v249
	v_cvt_pk_bf16_f32 v98, v146, v147
	v_mfma_f32_32x32x16_bf16 v[48:63], v[182:185], v[80:83], v[48:63]
	v_exp_f32_e32 v251, v251
	v_exp_f32_e32 v149, v149
	v_add_f32_e32 v253, v250, v148
	v_add_f32_e32 v252, v252, v253
	v_add_f32_e32 v253, v251, v149
	v_add_f32_e32 v252, v252, v253
	v_cvt_pk_bf16_f32 v107, v250, v251
	v_cvt_pk_bf16_f32 v99, v148, v149
	v_add_f32_e32 v131, v131, v252

.Lmb1_A_near:
	s_and_b64 vcc, exec, s[6:7]
	s_cbranch_vccnz .Lmb1_A_g0near
	s_add_i32 s45, s37, 1
	s_cmp_ge_u32 s45, s30
	s_cbranch_scc1 .Lmb1_skKAn
	s_add_i32 s45, s44, 0x2000
	s_and_b32 s45, s45, 0x6000
	s_add_i32 s45, s45, s74
	s_mov_b32 s99, m0
	s_mov_b32 m0, s45
	s_nop 0
	global_load_lds_dwordx4 v[114:115], off
	s_mov_b32 m0, s99
	s_mov_b32 s43, 1

.Lmb1_skVAn:
.Lmb1_A_g0near:
	s_waitcnt lgkmcnt(8)
	v_mfma_f32_32x32x16_bf16 v[16:31], v[108:111], v[186:189], v[16:31]
	v_mfma_f32_32x32x16_bf16 v[16:31], v[104:107], v[190:193], v[16:31]
	v_mfma_f32_32x32x16_bf16 v[16:31], v[100:103], v[194:197], v[16:31]
	v_mfma_f32_32x32x16_bf16 v[16:31], v[96:99], v[198:201], v[16:31]
	v_mfma_f32_32x32x16_bf16 v[32:47], v[108:111], v[202:205], v[32:47]
	v_mfma_f32_32x32x16_bf16 v[32:47], v[104:107], v[206:209], v[32:47]
	v_mfma_f32_32x32x16_bf16 v[32:47], v[100:103], v[210:213], v[32:47]
	v_mfma_f32_32x32x16_bf16 v[32:47], v[96:99], v[214:217], v[32:47]
	s_lshr_b32 s44, s34, 2
	s_cmp_eq_u32 s44, s91
	s_cselect_b64 s[8:9], -1, 0
	s_lshl_b32 s44, 1, s44
	v_and_b32_e32 v96, s44, v129
	v_cmp_ne_u32_e32 vcc, 0, v96
	s_or_b64 vcc, s[8:9], vcc
	s_nop 0
	v_cndmask_b32_e32 v96, v127, v112, vcc
	v_lshl_add_u32 v96, v96, 2, 0
	v_add_u32_e32 v104, 0x1d000, v96
	ds_read2_b32 v[96:97], v104 offset0:58 offset1:59
	ds_read2_b32 v[98:99], v104 offset0:26 offset1:27
	ds_read2_b32 v[100:101], v104 offset0:56 offset1:57
	s_waitcnt lgkmcnt(2)
	v_pk_add_f32 v[64:65], v[64:65], v[96:97] op_sel:[0,1] op_sel_hi:[1,0]
	ds_read2_b32 v[96:97], v104 offset0:24 offset1:25
	s_waitcnt lgkmcnt(2)
	v_pk_add_f32 v[48:49], v[48:49], v[98:99] op_sel:[0,1] op_sel_hi:[1,0]
	ds_read2_b32 v[98:99], v104 offset0:50 offset1:51
	s_waitcnt lgkmcnt(2)
	v_pk_add_f32 v[66:67], v[66:67], v[100:101] op_sel:[0,1] op_sel_hi:[1,0]
	ds_read2_b32 v[100:101], v104 offset0:18 offset1:19
	s_waitcnt lgkmcnt(1)
	v_pk_add_f32 v[68:69], v[68:69], v[98:99] op_sel:[0,1] op_sel_hi:[1,0]
	ds_read2_b32 v[98:99], v104 offset0:16 offset1:17
	s_waitcnt lgkmcnt(1)
	v_pk_add_f32 v[52:53], v[52:53], v[100:101] op_sel:[0,1] op_sel_hi:[1,0]
	ds_read2_b32 v[100:101], v104 offset0:42 offset1:43
	v_pk_add_f32 v[50:51], v[50:51], v[96:97] op_sel:[0,1] op_sel_hi:[1,0]
	ds_read2_b32 v[96:97], v104 offset0:48 offset1:49
	s_waitcnt lgkmcnt(1)
	v_pk_add_f32 v[72:73], v[72:73], v[100:101] op_sel:[0,1] op_sel_hi:[1,0]
	ds_read2_b32 v[100:101], v104 offset0:8 offset1:9
	s_waitcnt lgkmcnt(1)
	v_pk_add_f32 v[70:71], v[70:71], v[96:97] op_sel:[0,1] op_sel_hi:[1,0]
	ds_read2_b32 v[96:97], v104 offset0:10 offset1:11
	v_pk_add_f32 v[54:55], v[54:55], v[98:99] op_sel:[0,1] op_sel_hi:[1,0]
	ds_read2_b32 v[98:99], v104 offset0:40 offset1:41
	s_waitcnt lgkmcnt(2)
	v_pk_add_f32 v[58:59], v[58:59], v[100:101] op_sel:[0,1] op_sel_hi:[1,0]
	s_waitcnt lgkmcnt(1)
	v_pk_add_f32 v[56:57], v[56:57], v[96:97] op_sel:[0,1] op_sel_hi:[1,0]
	ds_read2_b32 v[96:97], v104 offset0:34 offset1:35
	s_waitcnt lgkmcnt(1)
	v_pk_add_f32 v[74:75], v[74:75], v[98:99] op_sel:[0,1] op_sel_hi:[1,0]
	ds_read2_b32 v[98:99], v104 offset0:2 offset1:3
	ds_read2_b32 v[102:103], v104 offset0:32 offset1:33
	ds_read2_b32 v[104:105], v104 offset1:1
	s_waitcnt lgkmcnt(3)
	v_pk_add_f32 v[76:77], v[76:77], v[96:97] op_sel:[0,1] op_sel_hi:[1,0]
	s_waitcnt lgkmcnt(2)
	v_pk_add_f32 v[60:61], v[60:61], v[98:99] op_sel:[0,1] op_sel_hi:[1,0]
	s_waitcnt lgkmcnt(1)
	v_pk_add_f32 v[78:79], v[78:79], v[102:103] op_sel:[0,1] op_sel_hi:[1,0]
	s_waitcnt lgkmcnt(0)
	v_pk_add_f32 v[62:63], v[62:63], v[104:105] op_sel:[0,1] op_sel_hi:[1,0]
	s_waitcnt lgkmcnt(0)
	v_mfma_f32_32x32x16_bf16 v[236:251], v[154:157], v[92:95], v[220:235]
	ds_read_b64_tr_b16 v[186:187], v218
	ds_read_b64_tr_b16 v[188:189], v218 offset:512
	ds_read_b64_tr_b16 v[190:191], v218 offset:1024
	ds_read_b64_tr_b16 v[192:193], v218 offset:1536
	ds_read_b64_tr_b16 v[194:195], v218 offset:2048
	ds_read_b64_tr_b16 v[196:197], v218 offset:2560
	ds_read_b64_tr_b16 v[198:199], v218 offset:3072
	ds_read_b64_tr_b16 v[200:201], v218 offset:3584
	ds_read_b64_tr_b16 v[202:203], v218 offset:4096
	ds_read_b64_tr_b16 v[204:205], v218 offset:4608
	ds_read_b64_tr_b16 v[206:207], v218 offset:5120
	v_mfma_f32_32x32x16_bf16 v[134:149], v[158:161], v[92:95], v[220:235]
	ds_read_b64_tr_b16 v[208:209], v218 offset:5632
	ds_read_b64_tr_b16 v[210:211], v218 offset:6144
	ds_read_b64_tr_b16 v[212:213], v218 offset:6656
	ds_read_b64_tr_b16 v[214:215], v218 offset:7168
	ds_read_b64_tr_b16 v[216:217], v218 offset:7680
	v_exp_f32_e32 v64, v64
	v_exp_f32_e32 v48, v48
	v_exp_f32_e32 v65, v65
	v_exp_f32_e32 v49, v49
	v_exp_f32_e32 v66, v66
	v_exp_f32_e32 v50, v50
	v_mfma_f32_32x32x16_bf16 v[236:251], v[162:165], v[88:91], v[236:251]
	v_exp_f32_e32 v67, v67
	v_exp_f32_e32 v51, v51
	v_add_f32_e32 v252, v48, v64
	v_exp_f32_e32 v68, v68
	v_exp_f32_e32 v52, v52
	v_add_f32_e32 v252, 0, v252
	v_add_f32_e32 v253, v49, v65
	v_exp_f32_e32 v69, v69
	v_exp_f32_e32 v53, v53
	v_add_f32_e32 v252, v253, v252
	v_add_f32_e32 v253, v50, v66
	v_mfma_f32_32x32x16_bf16 v[134:149], v[166:169], v[88:91], v[134:149]
	v_exp_f32_e32 v70, v70
	v_exp_f32_e32 v54, v54
	v_add_f32_e32 v252, v253, v252
	v_add_f32_e32 v253, v51, v67
	v_exp_f32_e32 v71, v71
	v_exp_f32_e32 v55, v55
	v_add_f32_e32 v252, v253, v252
	v_add_f32_e32 v253, v52, v68
	v_exp_f32_e32 v72, v72
	v_exp_f32_e32 v56, v56
	v_add_f32_e32 v252, v253, v252
	v_mfma_f32_32x32x16_bf16 v[236:251], v[170:173], v[84:87], v[236:251]
	v_add_f32_e32 v253, v53, v69
	v_exp_f32_e32 v73, v73
	v_exp_f32_e32 v57, v57
	v_add_f32_e32 v252, v253, v252
	v_add_f32_e32 v253, v54, v70
	v_exp_f32_e32 v74, v74
	v_exp_f32_e32 v58, v58
	v_add_f32_e32 v252, v253, v252
	v_add_f32_e32 v253, v55, v71
	v_exp_f32_e32 v75, v75
	v_exp_f32_e32 v59, v59
	v_mfma_f32_32x32x16_bf16 v[134:149], v[174:177], v[84:87], v[134:149]
	v_add_f32_e32 v252, v253, v252
	v_add_f32_e32 v253, v56, v72
	v_exp_f32_e32 v76, v76
	v_exp_f32_e32 v60, v60
	v_add_f32_e32 v252, v253, v252
	v_add_f32_e32 v253, v57, v73
	v_exp_f32_e32 v77, v77
	v_exp_f32_e32 v61, v61
	v_add_f32_e32 v252, v253, v252
	v_add_f32_e32 v253, v58, v74
	v_exp_f32_e32 v78, v78
	v_mfma_f32_32x32x16_bf16 v[236:251], v[178:181], v[80:83], v[236:251]
	v_exp_f32_e32 v62, v62
	v_add_f32_e32 v252, v253, v252
	v_add_f32_e32 v253, v59, v75
	v_exp_f32_e32 v79, v79
	v_exp_f32_e32 v63, v63
	v_add_f32_e32 v252, v253, v252
	v_add_f32_e32 v253, v60, v76
	v_add_f32_e32 v252, v253, v252
	v_add_f32_e32 v253, v61, v77
	v_add_f32_e32 v252, v253, v252
	v_add_f32_e32 v253, v62, v78
	v_mfma_f32_32x32x16_bf16 v[134:149], v[182:185], v[80:83], v[134:149]
	v_add_f32_e32 v252, v253, v252
	v_add_f32_e32 v253, v63, v79
	v_add_f32_e32 v252, v253, v252
	v_add_f32_e32 v131, v131, v252
	v_cvt_pk_bf16_f32 v108, v64, v65
	v_cvt_pk_bf16_f32 v109, v66, v67
	v_cvt_pk_bf16_f32 v110, v68, v69
	v_cvt_pk_bf16_f32 v111, v70, v71
	v_cvt_pk_bf16_f32 v104, v72, v73
	v_cvt_pk_bf16_f32 v105, v74, v75
	v_cvt_pk_bf16_f32 v106, v76, v77
	v_cvt_pk_bf16_f32 v107, v78, v79
	v_cvt_pk_bf16_f32 v100, v48, v49
	v_cvt_pk_bf16_f32 v101, v50, v51
	v_cvt_pk_bf16_f32 v102, v52, v53
	v_cvt_pk_bf16_f32 v103, v54, v55
	v_cvt_pk_bf16_f32 v96, v56, v57
	v_cvt_pk_bf16_f32 v97, v58, v59
	v_cvt_pk_bf16_f32 v98, v60, v61
	v_cvt_pk_bf16_f32 v99, v62, v63
	s_branch .Lmb1_A_tail

.Lmb1_skVBn:
.Lmb1_B_g0near:
	s_waitcnt lgkmcnt(8)
	v_mfma_f32_32x32x16_bf16 v[16:31], v[108:111], v[186:189], v[16:31]
	v_mfma_f32_32x32x16_bf16 v[16:31], v[104:107], v[190:193], v[16:31]
	v_mfma_f32_32x32x16_bf16 v[16:31], v[100:103], v[194:197], v[16:31]
	v_mfma_f32_32x32x16_bf16 v[16:31], v[96:99], v[198:201], v[16:31]
	v_mfma_f32_32x32x16_bf16 v[32:47], v[108:111], v[202:205], v[32:47]
	v_mfma_f32_32x32x16_bf16 v[32:47], v[104:107], v[206:209], v[32:47]
	v_mfma_f32_32x32x16_bf16 v[32:47], v[100:103], v[210:213], v[32:47]
	v_mfma_f32_32x32x16_bf16 v[32:47], v[96:99], v[214:217], v[32:47]
	s_lshr_b32 s44, s34, 2
	s_cmp_eq_u32 s44, s91
	s_cselect_b64 s[8:9], -1, 0
	s_lshl_b32 s44, 1, s44
	v_and_b32_e32 v96, s44, v129
	v_cmp_ne_u32_e32 vcc, 0, v96
	s_or_b64 vcc, s[8:9], vcc
	s_nop 0
	v_cndmask_b32_e32 v96, v127, v112, vcc
	v_lshl_add_u32 v96, v96, 2, 0
	v_add_u32_e32 v104, 0x1d000, v96
	ds_read2_b32 v[96:97], v104 offset0:58 offset1:59
	ds_read2_b32 v[98:99], v104 offset0:26 offset1:27
	ds_read2_b32 v[100:101], v104 offset0:56 offset1:57
	s_waitcnt lgkmcnt(2)
	v_pk_add_f32 v[236:237], v[236:237], v[96:97] op_sel:[0,1] op_sel_hi:[1,0]
	ds_read2_b32 v[96:97], v104 offset0:24 offset1:25
	s_waitcnt lgkmcnt(2)
	v_pk_add_f32 v[134:135], v[134:135], v[98:99] op_sel:[0,1] op_sel_hi:[1,0]
	ds_read2_b32 v[98:99], v104 offset0:50 offset1:51
	s_waitcnt lgkmcnt(2)
	v_pk_add_f32 v[238:239], v[238:239], v[100:101] op_sel:[0,1] op_sel_hi:[1,0]
	ds_read2_b32 v[100:101], v104 offset0:18 offset1:19
	s_waitcnt lgkmcnt(1)
	v_pk_add_f32 v[240:241], v[240:241], v[98:99] op_sel:[0,1] op_sel_hi:[1,0]
	ds_read2_b32 v[98:99], v104 offset0:16 offset1:17
	s_waitcnt lgkmcnt(1)
	v_pk_add_f32 v[138:139], v[138:139], v[100:101] op_sel:[0,1] op_sel_hi:[1,0]
	ds_read2_b32 v[100:101], v104 offset0:42 offset1:43
	v_pk_add_f32 v[136:137], v[136:137], v[96:97] op_sel:[0,1] op_sel_hi:[1,0]
	ds_read2_b32 v[96:97], v104 offset0:48 offset1:49
	s_waitcnt lgkmcnt(1)
	v_pk_add_f32 v[244:245], v[244:245], v[100:101] op_sel:[0,1] op_sel_hi:[1,0]
	ds_read2_b32 v[100:101], v104 offset0:8 offset1:9
	s_waitcnt lgkmcnt(1)
	v_pk_add_f32 v[242:243], v[242:243], v[96:97] op_sel:[0,1] op_sel_hi:[1,0]
	ds_read2_b32 v[96:97], v104 offset0:10 offset1:11
	v_pk_add_f32 v[140:141], v[140:141], v[98:99] op_sel:[0,1] op_sel_hi:[1,0]
	ds_read2_b32 v[98:99], v104 offset0:40 offset1:41
	s_waitcnt lgkmcnt(2)
	v_pk_add_f32 v[144:145], v[144:145], v[100:101] op_sel:[0,1] op_sel_hi:[1,0]
	s_waitcnt lgkmcnt(1)
	v_pk_add_f32 v[142:143], v[142:143], v[96:97] op_sel:[0,1] op_sel_hi:[1,0]
	ds_read2_b32 v[96:97], v104 offset0:34 offset1:35
	s_waitcnt lgkmcnt(1)
	v_pk_add_f32 v[246:247], v[246:247], v[98:99] op_sel:[0,1] op_sel_hi:[1,0]
	ds_read2_b32 v[98:99], v104 offset0:2 offset1:3
	ds_read2_b32 v[102:103], v104 offset0:32 offset1:33
	ds_read2_b32 v[104:105], v104 offset1:1
	s_waitcnt lgkmcnt(3)
	v_pk_add_f32 v[248:249], v[248:249], v[96:97] op_sel:[0,1] op_sel_hi:[1,0]
	s_waitcnt lgkmcnt(2)
	v_pk_add_f32 v[146:147], v[146:147], v[98:99] op_sel:[0,1] op_sel_hi:[1,0]
	s_waitcnt lgkmcnt(1)
	v_pk_add_f32 v[250:251], v[250:251], v[102:103] op_sel:[0,1] op_sel_hi:[1,0]
	s_waitcnt lgkmcnt(0)
	v_pk_add_f32 v[148:149], v[148:149], v[104:105] op_sel:[0,1] op_sel_hi:[1,0]
	s_waitcnt lgkmcnt(0)
; #define ATT_LAS __attribute__((address_space(3)))
; #define ATT_MFMA(a, b, c) __builtin_amdgcn_mfma_f32_32x32x16_bf16((a), (b), (c), 0, 0, 0)
; __device__ __forceinline__ void qkt(f32x16& p0, f32x16& p1, lds_cptr kb, const bf16x8* qr, const f32x16& z) {
; #pragma unroll
;     for (int d0 = 0; d0 < 4; ++d0) {
;         const bf16x8 b0 = *(const ATT_LAS bf16x8*)(kb + d0 * 2048);
;         const bf16x8 b1 = *(const ATT_LAS bf16x8*)(kb + d0 * 2048 + 512);
;         if (d0 == 0) { p0 = ATT_MFMA(b0, qr[0], z); p1 = ATT_MFMA(b1, qr[0], z); }
;         else { p0 = ATT_MFMA(b0, qr[d0], p0); p1 = ATT_MFMA(b1, qr[d0], p1); } }
	v_mfma_f32_32x32x16_bf16 v[64:79], v[154:157], v[92:95], v[220:235]
	ds_read_b64_tr_b16 v[186:187], v218
	ds_read_b64_tr_b16 v[188:189], v218 offset:512
	ds_read_b64_tr_b16 v[190:191], v218 offset:1024
	ds_read_b64_tr_b16 v[192:193], v218 offset:1536
	ds_read_b64_tr_b16 v[194:195], v218 offset:2048
	ds_read_b64_tr_b16 v[196:197], v218 offset:2560
	ds_read_b64_tr_b16 v[198:199], v218 offset:3072
	ds_read_b64_tr_b16 v[200:201], v218 offset:3584
	ds_read_b64_tr_b16 v[202:203], v218 offset:4096
	ds_read_b64_tr_b16 v[204:205], v218 offset:4608
	ds_read_b64_tr_b16 v[206:207], v218 offset:5120
	v_mfma_f32_32x32x16_bf16 v[48:63], v[158:161], v[92:95], v[220:235]
	ds_read_b64_tr_b16 v[208:209], v218 offset:5632
	ds_read_b64_tr_b16 v[210:211], v218 offset:6144
	ds_read_b64_tr_b16 v[212:213], v218 offset:6656
	ds_read_b64_tr_b16 v[214:215], v218 offset:7168
	ds_read_b64_tr_b16 v[216:217], v218 offset:7680
	v_exp_f32_e32 v236, v236
	v_exp_f32_e32 v134, v134
	v_exp_f32_e32 v237, v237
	v_exp_f32_e32 v135, v135
	v_exp_f32_e32 v238, v238
	v_exp_f32_e32 v136, v136
	v_mfma_f32_32x32x16_bf16 v[64:79], v[162:165], v[88:91], v[64:79]
	v_exp_f32_e32 v239, v239
	v_exp_f32_e32 v137, v137
	v_add_f32_e32 v252, v134, v236
	v_exp_f32_e32 v240, v240
	v_exp_f32_e32 v138, v138
	v_add_f32_e32 v252, 0, v252
	v_add_f32_e32 v253, v135, v237
	v_exp_f32_e32 v241, v241
	v_exp_f32_e32 v139, v139
	v_add_f32_e32 v252, v253, v252
	v_add_f32_e32 v253, v136, v238
	v_mfma_f32_32x32x16_bf16 v[48:63], v[166:169], v[88:91], v[48:63]
	v_exp_f32_e32 v242, v242
	v_exp_f32_e32 v140, v140
	v_add_f32_e32 v252, v253, v252
	v_add_f32_e32 v253, v137, v239
	v_exp_f32_e32 v243, v243
	v_exp_f32_e32 v141, v141
	v_add_f32_e32 v252, v253, v252
	v_add_f32_e32 v253, v138, v240
	v_exp_f32_e32 v244, v244
	v_exp_f32_e32 v142, v142
	v_add_f32_e32 v252, v253, v252
	v_mfma_f32_32x32x16_bf16 v[64:79], v[170:173], v[84:87], v[64:79]
	v_add_f32_e32 v253, v139, v241
	v_exp_f32_e32 v245, v245
	v_exp_f32_e32 v143, v143
	v_add_f32_e32 v252, v253, v252
	v_add_f32_e32 v253, v140, v242
	v_exp_f32_e32 v246, v246
	v_exp_f32_e32 v144, v144
	v_add_f32_e32 v252, v253, v252
	v_add_f32_e32 v253, v141, v243
	v_exp_f32_e32 v247, v247
	v_exp_f32_e32 v145, v145
	v_mfma_f32_32x32x16_bf16 v[48:63], v[174:177], v[84:87], v[48:63]
	v_add_f32_e32 v252, v253, v252
	v_add_f32_e32 v253, v142, v244
	v_exp_f32_e32 v248, v248
	v_exp_f32_e32 v146, v146
	v_add_f32_e32 v252, v253, v252
	v_add_f32_e32 v253, v143, v245
	v_exp_f32_e32 v249, v249
	v_exp_f32_e32 v147, v147
	v_add_f32_e32 v252, v253, v252
	v_add_f32_e32 v253, v144, v246
	v_exp_f32_e32 v250, v250
	v_mfma_f32_32x32x16_bf16 v[64:79], v[178:181], v[80:83], v[64:79]
	v_exp_f32_e32 v148, v148
	v_add_f32_e32 v252, v253, v252
	v_add_f32_e32 v253, v145, v247
	v_exp_f32_e32 v251, v251
	v_exp_f32_e32 v149, v149
	v_add_f32_e32 v252, v253, v252
	v_add_f32_e32 v253, v146, v248
	v_add_f32_e32 v252, v253, v252
	v_add_f32_e32 v253, v147, v249
	v_add_f32_e32 v252, v253, v252
	v_add_f32_e32 v253, v148, v250
	v_mfma_f32_32x32x16_bf16 v[48:63], v[182:185], v[80:83], v[48:63]
	v_add_f32_e32 v252, v253, v252
	v_add_f32_e32 v253, v149, v251
	v_add_f32_e32 v252, v253, v252
	v_add_f32_e32 v131, v131, v252
	v_cvt_pk_bf16_f32 v108, v236, v237
	v_cvt_pk_bf16_f32 v109, v238, v239
	v_cvt_pk_bf16_f32 v110, v240, v241
	v_cvt_pk_bf16_f32 v111, v242, v243
	v_cvt_pk_bf16_f32 v104, v244, v245
	v_cvt_pk_bf16_f32 v105, v246, v247
	v_cvt_pk_bf16_f32 v106, v248, v249
	v_cvt_pk_bf16_f32 v107, v250, v251
	v_cvt_pk_bf16_f32 v100, v134, v135
	v_cvt_pk_bf16_f32 v101, v136, v137
	v_cvt_pk_bf16_f32 v102, v138, v139
	v_cvt_pk_bf16_f32 v103, v140, v141
	v_cvt_pk_bf16_f32 v96, v142, v143
	v_cvt_pk_bf16_f32 v97, v144, v145
	v_cvt_pk_bf16_f32 v98, v146, v147
	v_cvt_pk_bf16_f32 v99, v148, v149
	s_branch .Lmb1_B_tail

.LBB0_2383:
.LBB0_2384:
.LBB0_2386:
.Lmb3_A:
	s_barrier
	s_and_b64 vcc, exec, s[6:7]
	s_cbranch_vccz .Lmb3_A_g1top
	s_add_i32 s42, s35, 1
	s_cmp_ge_u32 s42, s28
	s_cbranch_scc1 .Lmb3_skKA
	s_add_i32 s42, s43, 0x2000
	s_and_b32 s42, s42, 0x6000
	s_add_i32 s42, s42, s74
	s_mov_b32 s99, m0
	s_mov_b32 m0, s42
	s_nop 0
	global_load_lds_dwordx4 v[114:115], off
	s_mov_b32 m0, s99
	s_mov_b32 s37, 1

; __device__ __forceinline__ void pv(f32x16* o, int vb, bf16x8 pa0, bf16x8 pa1, bf16x8 pa2, bf16x8 pa3) {
; #pragma unroll
;     for (int d0 = 0; d0 < 2; ++d0) { s16x4 lo[4], hi[4];
; #pragma unroll
;         for (int ks = 0; ks < 4; ++ks) {
;             asm volatile("ds_read_b64_tr_b16 %0,%1 offset:%c2" : "=&v"(lo[ks]) : "v"(vb), "i"(d0 * 4096 + ks * 1024) : "memory");
;             asm volatile("ds_read_b64_tr_b16 %0,%1 offset:%c2" : "=&v"(hi[ks]) : "v"(vb), "i"(d0 * 4096 + ks * 1024 + 512) : "memory"); }
;         asm volatile("s_waitcnt lgkmcnt(0)" ::: "memory"); __builtin_amdgcn_sched_barrier(0);
.Lmb3_skVA:
.Lmb3_A_g1top:
	s_add_i32 s36, s43, 0x2000
	s_add_i32 s98, s43, 0x4000
	s_and_b32 s42, s98, 0x6000
	v_add_u32_e32 v133, s42, v130
	ds_read_b128 v[154:157], v133
	ds_read_b128 v[158:161], v133 offset:512
	ds_read_b128 v[162:165], v133 offset:2048
	ds_read_b128 v[166:169], v133 offset:2560
	ds_read_b128 v[170:173], v133 offset:4096
	ds_read_b128 v[174:177], v133 offset:4608
	ds_read_b128 v[178:181], v133 offset:6144
	ds_read_b128 v[182:185], v133 offset:6656
	s_and_b32 s42, s36, 0x6000
	v_add_u32_e32 v218, s42, v132
	s_add_i32 s98, s30, 2
	s_cmp_ge_i32 s30, s29
	s_cbranch_scc1 .Lmb3_A_near
	v_mfma_f32_32x32x16_bf16 v[16:31], v[108:111], v[186:189], v[16:31]
	v_exp_f32_e32 v64, v64
	v_exp_f32_e32 v48, v48
	v_mfma_f32_32x32x16_bf16 v[16:31], v[104:107], v[190:193], v[16:31]
	v_exp_f32_e32 v65, v65
	v_exp_f32_e32 v49, v49
	v_add_f32_e32 v252, v64, v48
	v_mfma_f32_32x32x16_bf16 v[16:31], v[100:103], v[194:197], v[16:31]
	v_exp_f32_e32 v66, v66
	v_exp_f32_e32 v50, v50
	v_add_f32_e32 v253, v65, v49
	v_add_f32_e32 v252, v252, v253
	v_mfma_f32_32x32x16_bf16 v[16:31], v[96:99], v[198:201], v[16:31]
	v_exp_f32_e32 v67, v67
	v_exp_f32_e32 v51, v51
	v_add_f32_e32 v253, v66, v50
	v_add_f32_e32 v252, v252, v253
	v_mfma_f32_32x32x16_bf16 v[32:47], v[108:111], v[202:205], v[32:47]
	v_exp_f32_e32 v68, v68
	v_exp_f32_e32 v52, v52
	v_add_f32_e32 v253, v67, v51
	v_add_f32_e32 v252, v252, v253
	ds_read_b64_tr_b16 v[186:187], v218
	ds_read_b64_tr_b16 v[188:189], v218 offset:512
	v_mfma_f32_32x32x16_bf16 v[32:47], v[104:107], v[206:209], v[32:47]
	v_exp_f32_e32 v69, v69
	v_exp_f32_e32 v53, v53
	v_add_f32_e32 v253, v68, v52
	v_add_f32_e32 v252, v252, v253
	ds_read_b64_tr_b16 v[190:191], v218 offset:1024
	ds_read_b64_tr_b16 v[192:193], v218 offset:1536
	v_mfma_f32_32x32x16_bf16 v[32:47], v[100:103], v[210:213], v[32:47]
	v_exp_f32_e32 v70, v70
	v_exp_f32_e32 v54, v54
	v_add_f32_e32 v253, v69, v53
	v_add_f32_e32 v252, v252, v253
	ds_read_b64_tr_b16 v[194:195], v218 offset:2048
	ds_read_b64_tr_b16 v[196:197], v218 offset:2560
	v_mfma_f32_32x32x16_bf16 v[32:47], v[96:99], v[214:217], v[32:47]
	v_exp_f32_e32 v71, v71
	v_exp_f32_e32 v55, v55
	v_add_f32_e32 v253, v70, v54
	v_add_f32_e32 v252, v252, v253
	ds_read_b64_tr_b16 v[198:199], v218 offset:3072
	ds_read_b64_tr_b16 v[200:201], v218 offset:3584
	s_and_b64 vcc, exec, s[6:7]
	s_cbranch_vccnz .Lmb3_A_g0mid
	s_add_i32 s42, s35, 1
	s_cmp_ge_u32 s42, s28
	s_cbranch_scc1 .Lmb3_skKAm
	s_add_i32 s42, s43, 0x2000
	s_and_b32 s42, s42, 0x6000
	s_add_i32 s42, s42, s74
	s_mov_b32 s99, m0
	s_mov_b32 m0, s42
	s_nop 0
	global_load_lds_dwordx4 v[114:115], off
	s_mov_b32 m0, s99
	s_mov_b32 s37, 1

.Lmb3_B:
	s_barrier
	s_and_b64 vcc, exec, s[6:7]
	s_cbranch_vccz .Lmb3_B_g1top
	s_add_i32 s42, s35, 1
	s_cmp_ge_u32 s42, s28
	s_cbranch_scc1 .Lmb3_skKB
	s_add_i32 s42, s43, 0x2000
	s_and_b32 s42, s42, 0x6000
	s_add_i32 s42, s42, s74
	s_mov_b32 s99, m0
	s_mov_b32 m0, s42
	s_nop 0
	global_load_lds_dwordx4 v[114:115], off
	s_mov_b32 m0, s99
	s_mov_b32 s37, 1

; __device__ __forceinline__ void pv(f32x16* o, int vb, bf16x8 pa0, bf16x8 pa1, bf16x8 pa2, bf16x8 pa3) {
; #pragma unroll
;     for (int d0 = 0; d0 < 2; ++d0) { s16x4 lo[4], hi[4];
; #pragma unroll
;         for (int ks = 0; ks < 4; ++ks) {
;             asm volatile("ds_read_b64_tr_b16 %0,%1 offset:%c2" : "=&v"(lo[ks]) : "v"(vb), "i"(d0 * 4096 + ks * 1024) : "memory");
;             asm volatile("ds_read_b64_tr_b16 %0,%1 offset:%c2" : "=&v"(hi[ks]) : "v"(vb), "i"(d0 * 4096 + ks * 1024 + 512) : "memory"); }
;         asm volatile("s_waitcnt lgkmcnt(0)" ::: "memory"); __builtin_amdgcn_sched_barrier(0);
.Lmb3_skVB:
.Lmb3_B_g1top:
	s_add_i32 s36, s43, 0x2000
	s_add_i32 s98, s43, 0x4000
	s_and_b32 s42, s98, 0x6000
	v_add_u32_e32 v133, s42, v130
	ds_read_b128 v[154:157], v133
	ds_read_b128 v[158:161], v133 offset:512
	ds_read_b128 v[162:165], v133 offset:2048
	ds_read_b128 v[166:169], v133 offset:2560
	ds_read_b128 v[170:173], v133 offset:4096
	ds_read_b128 v[174:177], v133 offset:4608
	ds_read_b128 v[178:181], v133 offset:6144
	ds_read_b128 v[182:185], v133 offset:6656
	s_and_b32 s42, s36, 0x6000
	v_add_u32_e32 v218, s42, v132
	s_add_i32 s98, s30, 2
	s_cmp_ge_i32 s30, s29
	s_cbranch_scc1 .Lmb3_B_near
	v_mfma_f32_32x32x16_bf16 v[16:31], v[108:111], v[186:189], v[16:31]
	v_exp_f32_e32 v236, v236
	v_exp_f32_e32 v134, v134
	v_mfma_f32_32x32x16_bf16 v[16:31], v[104:107], v[190:193], v[16:31]
	v_exp_f32_e32 v237, v237
	v_exp_f32_e32 v135, v135
	v_add_f32_e32 v252, v236, v134
	v_mfma_f32_32x32x16_bf16 v[16:31], v[100:103], v[194:197], v[16:31]
	v_exp_f32_e32 v238, v238
	v_exp_f32_e32 v136, v136
	v_add_f32_e32 v253, v237, v135
	v_add_f32_e32 v252, v252, v253
	v_mfma_f32_32x32x16_bf16 v[16:31], v[96:99], v[198:201], v[16:31]
	v_exp_f32_e32 v239, v239
	v_exp_f32_e32 v137, v137
	v_add_f32_e32 v253, v238, v136
	v_add_f32_e32 v252, v252, v253
	v_mfma_f32_32x32x16_bf16 v[32:47], v[108:111], v[202:205], v[32:47]
	v_exp_f32_e32 v240, v240
	v_exp_f32_e32 v138, v138
	v_add_f32_e32 v253, v239, v137
	v_add_f32_e32 v252, v252, v253
	ds_read_b64_tr_b16 v[186:187], v218
	ds_read_b64_tr_b16 v[188:189], v218 offset:512
	v_mfma_f32_32x32x16_bf16 v[32:47], v[104:107], v[206:209], v[32:47]
	v_exp_f32_e32 v241, v241
	v_exp_f32_e32 v139, v139
	v_add_f32_e32 v253, v240, v138
	v_add_f32_e32 v252, v252, v253
	ds_read_b64_tr_b16 v[190:191], v218 offset:1024
	ds_read_b64_tr_b16 v[192:193], v218 offset:1536
	v_mfma_f32_32x32x16_bf16 v[32:47], v[100:103], v[210:213], v[32:47]
	v_exp_f32_e32 v242, v242
	v_exp_f32_e32 v140, v140
	v_add_f32_e32 v253, v241, v139
	v_add_f32_e32 v252, v252, v253
	ds_read_b64_tr_b16 v[194:195], v218 offset:2048
	ds_read_b64_tr_b16 v[196:197], v218 offset:2560
	v_mfma_f32_32x32x16_bf16 v[32:47], v[96:99], v[214:217], v[32:47]
	v_exp_f32_e32 v243, v243
	v_exp_f32_e32 v141, v141
	v_add_f32_e32 v253, v242, v140
	v_add_f32_e32 v252, v252, v253
	ds_read_b64_tr_b16 v[198:199], v218 offset:3072
	ds_read_b64_tr_b16 v[200:201], v218 offset:3584
	s_and_b64 vcc, exec, s[6:7]
	s_cbranch_vccnz .Lmb3_B_g0mid
	s_add_i32 s42, s35, 1
	s_cmp_ge_u32 s42, s28
	s_cbranch_scc1 .Lmb3_skKBm
	s_add_i32 s42, s43, 0x2000
	s_and_b32 s42, s42, 0x6000
	s_add_i32 s42, s42, s74
	s_mov_b32 s99, m0
	s_mov_b32 m0, s42
	s_nop 0
	global_load_lds_dwordx4 v[114:115], off
	s_mov_b32 m0, s99
	s_mov_b32 s37, 1

.Lmb3_A_near:
	s_and_b64 vcc, exec, s[6:7]
	s_cbranch_vccnz .Lmb3_A_g0near
	s_add_i32 s42, s35, 1
	s_cmp_ge_u32 s42, s28
	s_cbranch_scc1 .Lmb3_skKAn
	s_add_i32 s42, s43, 0x2000
	s_and_b32 s42, s42, 0x6000
	s_add_i32 s42, s42, s74
	s_mov_b32 s99, m0
	s_mov_b32 m0, s42
	s_nop 0
	global_load_lds_dwordx4 v[114:115], off
	s_mov_b32 m0, s99
	s_mov_b32 s37, 1

.Lmb3_skVAn:
.Lmb3_A_g0near:
	s_waitcnt lgkmcnt(8)
	v_mfma_f32_32x32x16_bf16 v[16:31], v[108:111], v[186:189], v[16:31]
	v_mfma_f32_32x32x16_bf16 v[16:31], v[104:107], v[190:193], v[16:31]
	v_mfma_f32_32x32x16_bf16 v[16:31], v[100:103], v[194:197], v[16:31]
	v_mfma_f32_32x32x16_bf16 v[16:31], v[96:99], v[198:201], v[16:31]
	v_mfma_f32_32x32x16_bf16 v[32:47], v[108:111], v[202:205], v[32:47]
	v_mfma_f32_32x32x16_bf16 v[32:47], v[104:107], v[206:209], v[32:47]
	v_mfma_f32_32x32x16_bf16 v[32:47], v[100:103], v[210:213], v[32:47]
	v_mfma_f32_32x32x16_bf16 v[32:47], v[96:99], v[214:217], v[32:47]
	s_lshr_b32 s42, s30, 2
	s_cmp_eq_u32 s42, s93
	s_cselect_b64 s[10:11], -1, 0
	s_lshl_b32 s42, 1, s42
	v_and_b32_e32 v96, s42, v129
	v_cmp_ne_u32_e32 vcc, 0, v96
	s_or_b64 vcc, s[10:11], vcc
	s_nop 0
	v_cndmask_b32_e32 v96, v127, v112, vcc
	v_lshl_add_u32 v96, v96, 2, 0
	v_add_u32_e32 v104, 0x1d000, v96
	ds_read2_b32 v[96:97], v104 offset0:58 offset1:59
	ds_read2_b32 v[98:99], v104 offset0:26 offset1:27
	ds_read2_b32 v[100:101], v104 offset0:56 offset1:57
	s_waitcnt lgkmcnt(2)
	v_pk_add_f32 v[64:65], v[64:65], v[96:97] op_sel:[0,1] op_sel_hi:[1,0]
	ds_read2_b32 v[96:97], v104 offset0:24 offset1:25
	s_waitcnt lgkmcnt(2)
	v_pk_add_f32 v[48:49], v[48:49], v[98:99] op_sel:[0,1] op_sel_hi:[1,0]
	ds_read2_b32 v[98:99], v104 offset0:50 offset1:51
	s_waitcnt lgkmcnt(2)
	v_pk_add_f32 v[66:67], v[66:67], v[100:101] op_sel:[0,1] op_sel_hi:[1,0]
	ds_read2_b32 v[100:101], v104 offset0:18 offset1:19
	s_waitcnt lgkmcnt(1)
	v_pk_add_f32 v[68:69], v[68:69], v[98:99] op_sel:[0,1] op_sel_hi:[1,0]
	ds_read2_b32 v[98:99], v104 offset0:16 offset1:17
	s_waitcnt lgkmcnt(1)
	v_pk_add_f32 v[52:53], v[52:53], v[100:101] op_sel:[0,1] op_sel_hi:[1,0]
	ds_read2_b32 v[100:101], v104 offset0:42 offset1:43
	v_pk_add_f32 v[50:51], v[50:51], v[96:97] op_sel:[0,1] op_sel_hi:[1,0]
	ds_read2_b32 v[96:97], v104 offset0:48 offset1:49
	s_waitcnt lgkmcnt(1)
	v_pk_add_f32 v[72:73], v[72:73], v[100:101] op_sel:[0,1] op_sel_hi:[1,0]
	ds_read2_b32 v[100:101], v104 offset0:8 offset1:9
	s_waitcnt lgkmcnt(1)
	v_pk_add_f32 v[70:71], v[70:71], v[96:97] op_sel:[0,1] op_sel_hi:[1,0]
	ds_read2_b32 v[96:97], v104 offset0:10 offset1:11
	v_pk_add_f32 v[54:55], v[54:55], v[98:99] op_sel:[0,1] op_sel_hi:[1,0]
	ds_read2_b32 v[98:99], v104 offset0:40 offset1:41
	s_waitcnt lgkmcnt(2)
	v_pk_add_f32 v[58:59], v[58:59], v[100:101] op_sel:[0,1] op_sel_hi:[1,0]
	s_waitcnt lgkmcnt(1)
	v_pk_add_f32 v[56:57], v[56:57], v[96:97] op_sel:[0,1] op_sel_hi:[1,0]
	ds_read2_b32 v[96:97], v104 offset0:34 offset1:35
	s_waitcnt lgkmcnt(1)
	v_pk_add_f32 v[74:75], v[74:75], v[98:99] op_sel:[0,1] op_sel_hi:[1,0]
	ds_read2_b32 v[98:99], v104 offset0:2 offset1:3
	ds_read2_b32 v[102:103], v104 offset0:32 offset1:33
	ds_read2_b32 v[104:105], v104 offset1:1
	s_waitcnt lgkmcnt(3)
	v_pk_add_f32 v[76:77], v[76:77], v[96:97] op_sel:[0,1] op_sel_hi:[1,0]
	s_waitcnt lgkmcnt(2)
	v_pk_add_f32 v[60:61], v[60:61], v[98:99] op_sel:[0,1] op_sel_hi:[1,0]
	s_waitcnt lgkmcnt(1)
	v_pk_add_f32 v[78:79], v[78:79], v[102:103] op_sel:[0,1] op_sel_hi:[1,0]
	s_waitcnt lgkmcnt(0)
	v_pk_add_f32 v[62:63], v[62:63], v[104:105] op_sel:[0,1] op_sel_hi:[1,0]
	s_waitcnt lgkmcnt(0)
	v_mfma_f32_32x32x16_bf16 v[236:251], v[154:157], v[92:95], v[220:235]
	ds_read_b64_tr_b16 v[186:187], v218
	ds_read_b64_tr_b16 v[188:189], v218 offset:512
	ds_read_b64_tr_b16 v[190:191], v218 offset:1024
	ds_read_b64_tr_b16 v[192:193], v218 offset:1536
	ds_read_b64_tr_b16 v[194:195], v218 offset:2048
	ds_read_b64_tr_b16 v[196:197], v218 offset:2560
	ds_read_b64_tr_b16 v[198:199], v218 offset:3072
	ds_read_b64_tr_b16 v[200:201], v218 offset:3584
	ds_read_b64_tr_b16 v[202:203], v218 offset:4096
	ds_read_b64_tr_b16 v[204:205], v218 offset:4608
	ds_read_b64_tr_b16 v[206:207], v218 offset:5120
	v_mfma_f32_32x32x16_bf16 v[134:149], v[158:161], v[92:95], v[220:235]
	ds_read_b64_tr_b16 v[208:209], v218 offset:5632
	ds_read_b64_tr_b16 v[210:211], v218 offset:6144
	ds_read_b64_tr_b16 v[212:213], v218 offset:6656
	ds_read_b64_tr_b16 v[214:215], v218 offset:7168
	ds_read_b64_tr_b16 v[216:217], v218 offset:7680
	v_exp_f32_e32 v64, v64
	v_exp_f32_e32 v48, v48
	v_exp_f32_e32 v65, v65
	v_exp_f32_e32 v49, v49
	v_exp_f32_e32 v66, v66
	v_exp_f32_e32 v50, v50
	v_mfma_f32_32x32x16_bf16 v[236:251], v[162:165], v[88:91], v[236:251]
	v_exp_f32_e32 v67, v67
	v_exp_f32_e32 v51, v51
	v_add_f32_e32 v252, v48, v64
	v_exp_f32_e32 v68, v68
	v_exp_f32_e32 v52, v52
	v_add_f32_e32 v252, 0, v252
	v_add_f32_e32 v253, v49, v65
	v_exp_f32_e32 v69, v69
	v_exp_f32_e32 v53, v53
	v_add_f32_e32 v252, v253, v252
	v_add_f32_e32 v253, v50, v66
	v_mfma_f32_32x32x16_bf16 v[134:149], v[166:169], v[88:91], v[134:149]
	v_exp_f32_e32 v70, v70
	v_exp_f32_e32 v54, v54
	v_add_f32_e32 v252, v253, v252
	v_add_f32_e32 v253, v51, v67
	v_exp_f32_e32 v71, v71
	v_exp_f32_e32 v55, v55
	v_add_f32_e32 v252, v253, v252
	v_add_f32_e32 v253, v52, v68
	v_exp_f32_e32 v72, v72
	v_exp_f32_e32 v56, v56
	v_add_f32_e32 v252, v253, v252
	v_mfma_f32_32x32x16_bf16 v[236:251], v[170:173], v[84:87], v[236:251]
	v_add_f32_e32 v253, v53, v69
	v_exp_f32_e32 v73, v73
	v_exp_f32_e32 v57, v57
	v_add_f32_e32 v252, v253, v252
	v_add_f32_e32 v253, v54, v70
	v_exp_f32_e32 v74, v74
	v_exp_f32_e32 v58, v58
	v_add_f32_e32 v252, v253, v252
	v_add_f32_e32 v253, v55, v71
	v_exp_f32_e32 v75, v75
	v_exp_f32_e32 v59, v59
	v_mfma_f32_32x32x16_bf16 v[134:149], v[174:177], v[84:87], v[134:149]
	v_add_f32_e32 v252, v253, v252
	v_add_f32_e32 v253, v56, v72
	v_exp_f32_e32 v76, v76
	v_exp_f32_e32 v60, v60
	v_add_f32_e32 v252, v253, v252
	v_add_f32_e32 v253, v57, v73
	v_exp_f32_e32 v77, v77
	v_exp_f32_e32 v61, v61
	v_add_f32_e32 v252, v253, v252
	v_add_f32_e32 v253, v58, v74
	v_exp_f32_e32 v78, v78
	v_mfma_f32_32x32x16_bf16 v[236:251], v[178:181], v[80:83], v[236:251]
	v_exp_f32_e32 v62, v62
	v_add_f32_e32 v252, v253, v252
	v_add_f32_e32 v253, v59, v75
	v_exp_f32_e32 v79, v79
	v_exp_f32_e32 v63, v63
	v_add_f32_e32 v252, v253, v252
	v_add_f32_e32 v253, v60, v76
	v_add_f32_e32 v252, v253, v252
	v_add_f32_e32 v253, v61, v77
	v_add_f32_e32 v252, v253, v252
	v_add_f32_e32 v253, v62, v78
	v_mfma_f32_32x32x16_bf16 v[134:149], v[182:185], v[80:83], v[134:149]
	v_add_f32_e32 v252, v253, v252
	v_add_f32_e32 v253, v63, v79
	v_add_f32_e32 v252, v253, v252
	v_add_f32_e32 v131, v131, v252
	v_cvt_pk_bf16_f32 v108, v64, v65
	v_cvt_pk_bf16_f32 v109, v66, v67
	v_cvt_pk_bf16_f32 v110, v68, v69
	v_cvt_pk_bf16_f32 v111, v70, v71
	v_cvt_pk_bf16_f32 v104, v72, v73
	v_cvt_pk_bf16_f32 v105, v74, v75
	v_cvt_pk_bf16_f32 v106, v76, v77
	v_cvt_pk_bf16_f32 v107, v78, v79
	v_cvt_pk_bf16_f32 v100, v48, v49
	v_cvt_pk_bf16_f32 v101, v50, v51
	v_cvt_pk_bf16_f32 v102, v52, v53
	v_cvt_pk_bf16_f32 v103, v54, v55
	v_cvt_pk_bf16_f32 v96, v56, v57
	v_cvt_pk_bf16_f32 v97, v58, v59
	v_cvt_pk_bf16_f32 v98, v60, v61
	v_cvt_pk_bf16_f32 v99, v62, v63
	s_branch .Lmb3_A_tail

.Lmb3_skVBn:
.Lmb3_B_g0near:
	s_waitcnt lgkmcnt(8)
	v_mfma_f32_32x32x16_bf16 v[16:31], v[108:111], v[186:189], v[16:31]
	v_mfma_f32_32x32x16_bf16 v[16:31], v[104:107], v[190:193], v[16:31]
	v_mfma_f32_32x32x16_bf16 v[16:31], v[100:103], v[194:197], v[16:31]
	v_mfma_f32_32x32x16_bf16 v[16:31], v[96:99], v[198:201], v[16:31]
	v_mfma_f32_32x32x16_bf16 v[32:47], v[108:111], v[202:205], v[32:47]
	v_mfma_f32_32x32x16_bf16 v[32:47], v[104:107], v[206:209], v[32:47]
	v_mfma_f32_32x32x16_bf16 v[32:47], v[100:103], v[210:213], v[32:47]
	v_mfma_f32_32x32x16_bf16 v[32:47], v[96:99], v[214:217], v[32:47]
	s_lshr_b32 s42, s30, 2
	s_cmp_eq_u32 s42, s93
	s_cselect_b64 s[10:11], -1, 0
	s_lshl_b32 s42, 1, s42
	v_and_b32_e32 v96, s42, v129
	v_cmp_ne_u32_e32 vcc, 0, v96
	s_or_b64 vcc, s[10:11], vcc
	s_nop 0
	v_cndmask_b32_e32 v96, v127, v112, vcc
	v_lshl_add_u32 v96, v96, 2, 0
	v_add_u32_e32 v104, 0x1d000, v96
	ds_read2_b32 v[96:97], v104 offset0:58 offset1:59
	ds_read2_b32 v[98:99], v104 offset0:26 offset1:27
	ds_read2_b32 v[100:101], v104 offset0:56 offset1:57
	s_waitcnt lgkmcnt(2)
	v_pk_add_f32 v[236:237], v[236:237], v[96:97] op_sel:[0,1] op_sel_hi:[1,0]
	ds_read2_b32 v[96:97], v104 offset0:24 offset1:25
	s_waitcnt lgkmcnt(2)
	v_pk_add_f32 v[134:135], v[134:135], v[98:99] op_sel:[0,1] op_sel_hi:[1,0]
	ds_read2_b32 v[98:99], v104 offset0:50 offset1:51
	s_waitcnt lgkmcnt(2)
	v_pk_add_f32 v[238:239], v[238:239], v[100:101] op_sel:[0,1] op_sel_hi:[1,0]
	ds_read2_b32 v[100:101], v104 offset0:18 offset1:19
	s_waitcnt lgkmcnt(1)
	v_pk_add_f32 v[240:241], v[240:241], v[98:99] op_sel:[0,1] op_sel_hi:[1,0]
	ds_read2_b32 v[98:99], v104 offset0:16 offset1:17
	s_waitcnt lgkmcnt(1)
	v_pk_add_f32 v[138:139], v[138:139], v[100:101] op_sel:[0,1] op_sel_hi:[1,0]
	ds_read2_b32 v[100:101], v104 offset0:42 offset1:43
	v_pk_add_f32 v[136:137], v[136:137], v[96:97] op_sel:[0,1] op_sel_hi:[1,0]
	ds_read2_b32 v[96:97], v104 offset0:48 offset1:49
	s_waitcnt lgkmcnt(1)
	v_pk_add_f32 v[244:245], v[244:245], v[100:101] op_sel:[0,1] op_sel_hi:[1,0]
	ds_read2_b32 v[100:101], v104 offset0:8 offset1:9
	s_waitcnt lgkmcnt(1)
	v_pk_add_f32 v[242:243], v[242:243], v[96:97] op_sel:[0,1] op_sel_hi:[1,0]
	ds_read2_b32 v[96:97], v104 offset0:10 offset1:11
	v_pk_add_f32 v[140:141], v[140:141], v[98:99] op_sel:[0,1] op_sel_hi:[1,0]
	ds_read2_b32 v[98:99], v104 offset0:40 offset1:41
	s_waitcnt lgkmcnt(2)
	v_pk_add_f32 v[144:145], v[144:145], v[100:101] op_sel:[0,1] op_sel_hi:[1,0]
	s_waitcnt lgkmcnt(1)
	v_pk_add_f32 v[142:143], v[142:143], v[96:97] op_sel:[0,1] op_sel_hi:[1,0]
	ds_read2_b32 v[96:97], v104 offset0:34 offset1:35
	s_waitcnt lgkmcnt(1)
	v_pk_add_f32 v[246:247], v[246:247], v[98:99] op_sel:[0,1] op_sel_hi:[1,0]
	ds_read2_b32 v[98:99], v104 offset0:2 offset1:3
	ds_read2_b32 v[102:103], v104 offset0:32 offset1:33
	ds_read2_b32 v[104:105], v104 offset1:1
	s_waitcnt lgkmcnt(3)
	v_pk_add_f32 v[248:249], v[248:249], v[96:97] op_sel:[0,1] op_sel_hi:[1,0]
	s_waitcnt lgkmcnt(2)
	v_pk_add_f32 v[146:147], v[146:147], v[98:99] op_sel:[0,1] op_sel_hi:[1,0]
	s_waitcnt lgkmcnt(1)
	v_pk_add_f32 v[250:251], v[250:251], v[102:103] op_sel:[0,1] op_sel_hi:[1,0]
	s_waitcnt lgkmcnt(0)
	v_pk_add_f32 v[148:149], v[148:149], v[104:105] op_sel:[0,1] op_sel_hi:[1,0]
	s_waitcnt lgkmcnt(0)
; #define ATT_LAS __attribute__((address_space(3)))
; #define ATT_MFMA(a, b, c) __builtin_amdgcn_mfma_f32_32x32x16_bf16((a), (b), (c), 0, 0, 0)
; __device__ __forceinline__ void qkt(f32x16& p0, f32x16& p1, lds_cptr kb, const bf16x8* qr, const f32x16& z) {
; #pragma unroll
;     for (int d0 = 0; d0 < 4; ++d0) {
;         const bf16x8 b0 = *(const ATT_LAS bf16x8*)(kb + d0 * 2048);
;         const bf16x8 b1 = *(const ATT_LAS bf16x8*)(kb + d0 * 2048 + 512);
;         if (d0 == 0) { p0 = ATT_MFMA(b0, qr[0], z); p1 = ATT_MFMA(b1, qr[0], z); }
;         else { p0 = ATT_MFMA(b0, qr[d0], p0); p1 = ATT_MFMA(b1, qr[d0], p1); } }
	v_mfma_f32_32x32x16_bf16 v[64:79], v[154:157], v[92:95], v[220:235]
	ds_read_b64_tr_b16 v[186:187], v218
	ds_read_b64_tr_b16 v[188:189], v218 offset:512
	ds_read_b64_tr_b16 v[190:191], v218 offset:1024
	ds_read_b64_tr_b16 v[192:193], v218 offset:1536
	ds_read_b64_tr_b16 v[194:195], v218 offset:2048
	ds_read_b64_tr_b16 v[196:197], v218 offset:2560
	ds_read_b64_tr_b16 v[198:199], v218 offset:3072
	ds_read_b64_tr_b16 v[200:201], v218 offset:3584
	ds_read_b64_tr_b16 v[202:203], v218 offset:4096
	ds_read_b64_tr_b16 v[204:205], v218 offset:4608
	ds_read_b64_tr_b16 v[206:207], v218 offset:5120
	v_mfma_f32_32x32x16_bf16 v[48:63], v[158:161], v[92:95], v[220:235]
	ds_read_b64_tr_b16 v[208:209], v218 offset:5632
	ds_read_b64_tr_b16 v[210:211], v218 offset:6144
	ds_read_b64_tr_b16 v[212:213], v218 offset:6656
	ds_read_b64_tr_b16 v[214:215], v218 offset:7168
	ds_read_b64_tr_b16 v[216:217], v218 offset:7680
	v_exp_f32_e32 v236, v236
	v_exp_f32_e32 v134, v134
	v_exp_f32_e32 v237, v237
	v_exp_f32_e32 v135, v135
	v_exp_f32_e32 v238, v238
	v_exp_f32_e32 v136, v136
	v_mfma_f32_32x32x16_bf16 v[64:79], v[162:165], v[88:91], v[64:79]
	v_exp_f32_e32 v239, v239
	v_exp_f32_e32 v137, v137
	v_add_f32_e32 v252, v134, v236
	v_exp_f32_e32 v240, v240
	v_exp_f32_e32 v138, v138
	v_add_f32_e32 v252, 0, v252
	v_add_f32_e32 v253, v135, v237
	v_exp_f32_e32 v241, v241
	v_exp_f32_e32 v139, v139
	v_add_f32_e32 v252, v253, v252
	v_add_f32_e32 v253, v136, v238
	v_mfma_f32_32x32x16_bf16 v[48:63], v[166:169], v[88:91], v[48:63]
	v_exp_f32_e32 v242, v242
	v_exp_f32_e32 v140, v140
	v_add_f32_e32 v252, v253, v252
	v_add_f32_e32 v253, v137, v239
	v_exp_f32_e32 v243, v243
	v_exp_f32_e32 v141, v141
	v_add_f32_e32 v252, v253, v252
	v_add_f32_e32 v253, v138, v240
	v_exp_f32_e32 v244, v244
	v_exp_f32_e32 v142, v142
	v_add_f32_e32 v252, v253, v252
	v_mfma_f32_32x32x16_bf16 v[64:79], v[170:173], v[84:87], v[64:79]
	v_add_f32_e32 v253, v139, v241
	v_exp_f32_e32 v245, v245
	v_exp_f32_e32 v143, v143
	v_add_f32_e32 v252, v253, v252
	v_add_f32_e32 v253, v140, v242
	v_exp_f32_e32 v246, v246
	v_exp_f32_e32 v144, v144
	v_add_f32_e32 v252, v253, v252
	v_add_f32_e32 v253, v141, v243
	v_exp_f32_e32 v247, v247
	v_exp_f32_e32 v145, v145
	v_mfma_f32_32x32x16_bf16 v[48:63], v[174:177], v[84:87], v[48:63]
	v_add_f32_e32 v252, v253, v252
	v_add_f32_e32 v253, v142, v244
	v_exp_f32_e32 v248, v248
	v_exp_f32_e32 v146, v146
	v_add_f32_e32 v252, v253, v252
	v_add_f32_e32 v253, v143, v245
	v_exp_f32_e32 v249, v249
	v_exp_f32_e32 v147, v147
	v_add_f32_e32 v252, v253, v252
	v_add_f32_e32 v253, v144, v246
	v_exp_f32_e32 v250, v250
	v_mfma_f32_32x32x16_bf16 v[64:79], v[178:181], v[80:83], v[64:79]
	v_exp_f32_e32 v148, v148
	v_add_f32_e32 v252, v253, v252
	v_add_f32_e32 v253, v145, v247
	v_exp_f32_e32 v251, v251
	v_exp_f32_e32 v149, v149
	v_add_f32_e32 v252, v253, v252
	v_add_f32_e32 v253, v146, v248
	v_add_f32_e32 v252, v253, v252
	v_add_f32_e32 v253, v147, v249
	v_add_f32_e32 v252, v253, v252
	v_add_f32_e32 v253, v148, v250
	v_mfma_f32_32x32x16_bf16 v[48:63], v[182:185], v[80:83], v[48:63]
	v_add_f32_e32 v252, v253, v252
	v_add_f32_e32 v253, v149, v251
	v_add_f32_e32 v252, v253, v252
	v_add_f32_e32 v131, v131, v252
	v_cvt_pk_bf16_f32 v108, v236, v237
	v_cvt_pk_bf16_f32 v109, v238, v239
	v_cvt_pk_bf16_f32 v110, v240, v241
	v_cvt_pk_bf16_f32 v111, v242, v243
	v_cvt_pk_bf16_f32 v104, v244, v245
	v_cvt_pk_bf16_f32 v105, v246, v247
	v_cvt_pk_bf16_f32 v106, v248, v249
	v_cvt_pk_bf16_f32 v107, v250, v251
	v_cvt_pk_bf16_f32 v100, v134, v135
	v_cvt_pk_bf16_f32 v101, v136, v137
	v_cvt_pk_bf16_f32 v102, v138, v139
	v_cvt_pk_bf16_f32 v103, v140, v141
	v_cvt_pk_bf16_f32 v96, v142, v143
	v_cvt_pk_bf16_f32 v97, v144, v145
	v_cvt_pk_bf16_f32 v98, v146, v147
	v_cvt_pk_bf16_f32 v99, v148, v149
	s_branch .Lmb3_B_tail
